# v25 + non-temporal stores for the two big write-once GEMM outputs (in-proj Z, mlp-up U) to keep L2 for GEMM operands
# speedup vs baseline: 1.0075x; 1.0075x over previous
.LBB0_696:
	v_add_u32_e32 v124, s0, v144
	v_mov_b64_e32 v[126:127], s[12:13]
	v_ashrrev_i32_e32 v125, 31, v124
	v_mad_i64_i32 v[126:127], s[0:1], v162, s2, v[126:127]
	v_lshl_add_u64 v[126:127], v[124:125], 1, v[126:127]
	v_cvt_pk_bf16_f32 v128, v148, v149
	v_cvt_pk_bf16_f32 v129, v150, v151
	v_cvt_pk_bf16_f32 v130, v152, v153
	v_cvt_pk_bf16_f32 v131, v154, v155
	s_cmp_lt_i32 s19, 2
	s_mov_b64 s[28:29], -1
	global_store_dwordx4 v[126:127], v[128:131], off nt
	s_cbranch_scc1 .LBB0_702
	s_cmp_gt_i32 s19, 2
	s_cbranch_scc0 .LBB0_699
	v_lshlrev_b32_e32 v180, 3, v161
	v_lshl_add_u64 v[128:129], s[14:15], 0, v[180:181]
	v_lshlrev_b32_e32 v180, 3, v159
	v_lshl_add_u64 v[128:129], v[128:129], 0, v[180:181]
	global_load_dwordx4 v[148:151], v[128:129], off offset:16
	s_nop 0
	global_load_dwordx4 v[128:131], v[128:129], off
	s_mov_b64 s[28:29], 0
	s_waitcnt vmcnt(0)
	v_pk_mul_f32 v[152:153], v[120:121], v[128:129] op_sel:[1,1] op_sel_hi:[1,0]
	s_nop 0
	v_pk_fma_f32 v[154:155], v[120:121], v[128:129], v[152:153] neg_lo:[0,0,1] neg_hi:[0,0,1]
	v_pk_fma_f32 v[128:129], v[120:121], v[128:129], v[152:153] op_sel_hi:[0,1,1]
	v_mov_b32_e32 v155, v129
	v_pk_mul_f32 v[128:129], v[146:147], v[154:155] op_sel_hi:[0,1]
	v_mul_f32_e32 v152, v123, v131
	v_mul_f32_e32 v154, v122, v131
	v_pk_fma_f32 v[152:153], v[122:123], v[130:131], v[152:153] op_sel_hi:[1,1,0] neg_lo:[0,0,1] neg_hi:[0,0,1]
	v_pk_fma_f32 v[130:131], v[122:123], v[130:131], v[154:155] op_sel:[0,1,0] op_sel_hi:[1,0,0]
	s_nop 0
	v_mov_b32_e32 v153, v131
	v_pk_mul_f32 v[130:131], v[146:147], v[152:153] op_sel_hi:[0,1]
	v_pk_mul_f32 v[152:153], v[116:117], v[148:149] op_sel:[1,1] op_sel_hi:[1,0]
	s_nop 0
	v_pk_fma_f32 v[154:155], v[116:117], v[148:149], v[152:153] neg_lo:[0,0,1] neg_hi:[0,0,1]
	v_pk_fma_f32 v[148:149], v[116:117], v[148:149], v[152:153] op_sel_hi:[0,1,1]
	v_mov_b32_e32 v155, v149
	v_pk_mul_f32 v[148:149], v[146:147], v[154:155] op_sel_hi:[0,1]
	v_mul_f32_e32 v152, v119, v151
	v_mul_f32_e32 v154, v118, v151
	v_pk_fma_f32 v[152:153], v[118:119], v[150:151], v[152:153] op_sel_hi:[1,1,0] neg_lo:[0,0,1] neg_hi:[0,0,1]
	v_pk_fma_f32 v[150:151], v[118:119], v[150:151], v[154:155] op_sel:[0,1,0] op_sel_hi:[1,0,0]
	s_nop 0
	v_mov_b32_e32 v153, v151
	v_pk_mul_f32 v[150:151], v[146:147], v[152:153] op_sel_hi:[0,1]

.LBB0_706:
	v_cvt_pk_bf16_f32 v116, v128, v129
	v_cvt_pk_bf16_f32 v117, v130, v131
	v_cvt_pk_bf16_f32 v118, v148, v149
	v_cvt_pk_bf16_f32 v119, v150, v151
	global_store_dwordx4 v[126:127], v[116:119], off offset:256 nt
	s_cmp_lt_i32 s19, 2
	s_mov_b64 s[28:29], -1
	v_mov_b32_e32 v116, v160
	s_nop 0
	v_add3_u32 v127, v116, s4, 16
	v_bitop3_b32 v116, v127, s86, v254 bitop3:0x6c
	v_cmp_gt_i32_e32 vcc, s86, v127
	v_add_u32_e32 v116, 0x100, v116
	s_nop 0
	v_cndmask_b32_sdwa v116, v116, v127, vcc dst_sel:DWORD dst_unused:UNUSED_PAD src0_sel:DWORD src1_sel:BYTE_0
	v_lshlrev_b32_e32 v126, 5, v116
	s_cbranch_scc1 .LBB0_712
	s_cmp_gt_i32 s19, 2
	s_cbranch_scc0 .LBB0_709
	v_lshlrev_b32_e32 v180, 3, v126
	v_lshl_add_u64 v[116:117], s[14:15], 0, v[180:181]
	v_lshlrev_b32_e32 v180, 3, v159
	v_lshl_add_u64 v[116:117], v[116:117], 0, v[180:181]
	global_load_dwordx4 v[120:123], v[116:117], off offset:16
	s_nop 0
	global_load_dwordx4 v[116:119], v[116:117], off
	s_mov_b64 s[28:29], 0
	s_waitcnt vmcnt(0)
	v_pk_mul_f32 v[128:129], v[112:113], v[116:117] op_sel:[1,1] op_sel_hi:[1,0]
	s_nop 0
	v_pk_fma_f32 v[130:131], v[112:113], v[116:117], v[128:129] neg_lo:[0,0,1] neg_hi:[0,0,1]
	v_pk_fma_f32 v[116:117], v[112:113], v[116:117], v[128:129] op_sel_hi:[0,1,1]
	v_mov_b32_e32 v131, v117
	v_pk_mul_f32 v[116:117], v[146:147], v[130:131] op_sel_hi:[0,1]
	v_mul_f32_e32 v128, v115, v119
	v_mul_f32_e32 v130, v114, v119
	v_pk_fma_f32 v[128:129], v[114:115], v[118:119], v[128:129] op_sel_hi:[1,1,0] neg_lo:[0,0,1] neg_hi:[0,0,1]
	v_pk_fma_f32 v[118:119], v[114:115], v[118:119], v[130:131] op_sel:[0,1,0] op_sel_hi:[1,0,0]
	s_nop 0
	v_mov_b32_e32 v129, v119
	v_pk_mul_f32 v[118:119], v[146:147], v[128:129] op_sel_hi:[0,1]
	v_pk_mul_f32 v[128:129], v[108:109], v[120:121] op_sel:[1,1] op_sel_hi:[1,0]
	s_nop 0
	v_pk_fma_f32 v[130:131], v[108:109], v[120:121], v[128:129] neg_lo:[0,0,1] neg_hi:[0,0,1]
	v_pk_fma_f32 v[120:121], v[108:109], v[120:121], v[128:129] op_sel_hi:[0,1,1]
	v_mov_b32_e32 v131, v121
	v_pk_mul_f32 v[120:121], v[146:147], v[130:131] op_sel_hi:[0,1]
	v_mul_f32_e32 v128, v111, v123
	v_mul_f32_e32 v130, v110, v123
	v_pk_fma_f32 v[128:129], v[110:111], v[122:123], v[128:129] op_sel_hi:[1,1,0] neg_lo:[0,0,1] neg_hi:[0,0,1]
	v_pk_fma_f32 v[122:123], v[110:111], v[122:123], v[130:131] op_sel:[0,1,0] op_sel_hi:[1,0,0]
	s_nop 0
	v_mov_b32_e32 v129, v123
	v_pk_mul_f32 v[122:123], v[146:147], v[128:129] op_sel_hi:[0,1]

.LBB0_716:
	v_mov_b64_e32 v[108:109], s[12:13]
	v_mad_i64_i32 v[108:109], s[0:1], v127, s2, v[108:109]
	v_lshl_add_u64 v[108:109], v[124:125], 1, v[108:109]
	v_cvt_pk_bf16_f32 v110, v116, v117
	v_cvt_pk_bf16_f32 v111, v118, v119
	v_cvt_pk_bf16_f32 v112, v120, v121
	v_cvt_pk_bf16_f32 v113, v122, v123
	s_cmp_lt_i32 s19, 2
	s_mov_b64 s[28:29], -1
	global_store_dwordx4 v[108:109], v[110:113], off nt
	s_cbranch_scc1 .LBB0_722
	s_cmp_gt_i32 s19, 2
	s_cbranch_scc0 .LBB0_719
	v_lshlrev_b32_e32 v180, 3, v126
	v_lshl_add_u64 v[110:111], s[14:15], 0, v[180:181]
	v_lshlrev_b32_e32 v180, 3, v159
	v_lshl_add_u64 v[110:111], v[110:111], 0, v[180:181]
	global_load_dwordx4 v[114:117], v[110:111], off offset:16
	s_nop 0
	global_load_dwordx4 v[110:113], v[110:111], off
	s_mov_b64 s[28:29], 0
	s_waitcnt vmcnt(0)
	v_pk_mul_f32 v[118:119], v[104:105], v[110:111] op_sel:[1,1] op_sel_hi:[1,0]
	s_nop 0
	v_pk_fma_f32 v[120:121], v[104:105], v[110:111], v[118:119] neg_lo:[0,0,1] neg_hi:[0,0,1]
	v_pk_fma_f32 v[110:111], v[104:105], v[110:111], v[118:119] op_sel_hi:[0,1,1]
	v_mov_b32_e32 v121, v111
	v_pk_mul_f32 v[110:111], v[146:147], v[120:121] op_sel_hi:[0,1]
	v_mul_f32_e32 v118, v107, v113
	v_mul_f32_e32 v120, v106, v113
	v_pk_fma_f32 v[118:119], v[106:107], v[112:113], v[118:119] op_sel_hi:[1,1,0] neg_lo:[0,0,1] neg_hi:[0,0,1]
	v_pk_fma_f32 v[112:113], v[106:107], v[112:113], v[120:121] op_sel:[0,1,0] op_sel_hi:[1,0,0]
	s_nop 0
	v_mov_b32_e32 v119, v113
	v_pk_mul_f32 v[112:113], v[146:147], v[118:119] op_sel_hi:[0,1]
	v_pk_mul_f32 v[118:119], v[100:101], v[114:115] op_sel:[1,1] op_sel_hi:[1,0]
	s_nop 0
	v_pk_fma_f32 v[120:121], v[100:101], v[114:115], v[118:119] neg_lo:[0,0,1] neg_hi:[0,0,1]
	v_pk_fma_f32 v[114:115], v[100:101], v[114:115], v[118:119] op_sel_hi:[0,1,1]
	v_mov_b32_e32 v121, v115
	v_pk_mul_f32 v[114:115], v[146:147], v[120:121] op_sel_hi:[0,1]
	v_mul_f32_e32 v118, v103, v117
	v_mul_f32_e32 v120, v102, v117
	v_pk_fma_f32 v[118:119], v[102:103], v[116:117], v[118:119] op_sel_hi:[1,1,0] neg_lo:[0,0,1] neg_hi:[0,0,1]
	v_pk_fma_f32 v[116:117], v[102:103], v[116:117], v[120:121] op_sel:[0,1,0] op_sel_hi:[1,0,0]
	s_nop 0
	v_mov_b32_e32 v119, v117
	v_pk_mul_f32 v[116:117], v[146:147], v[118:119] op_sel_hi:[0,1]

.LBB0_726:
	v_cvt_pk_bf16_f32 v100, v110, v111
	v_cvt_pk_bf16_f32 v101, v112, v113
	v_cvt_pk_bf16_f32 v102, v114, v115
	v_cvt_pk_bf16_f32 v103, v116, v117
	global_store_dwordx4 v[108:109], v[100:103], off offset:256 nt
	s_cmp_lt_i32 s19, 2
	s_mov_b64 s[28:29], -1
	v_mov_b32_e32 v100, v160
	s_nop 0
	v_add3_u32 v109, v100, s4, 32
	v_bitop3_b32 v100, v109, s86, v254 bitop3:0x6c
	v_cmp_gt_i32_e32 vcc, s86, v109
	v_add_u32_e32 v100, 0x100, v100
	s_nop 0
	v_cndmask_b32_sdwa v100, v100, v109, vcc dst_sel:DWORD dst_unused:UNUSED_PAD src0_sel:DWORD src1_sel:BYTE_0
	v_lshlrev_b32_e32 v108, 5, v100
	s_cbranch_scc1 .LBB0_732
	s_cmp_gt_i32 s19, 2
	s_cbranch_scc0 .LBB0_729
	v_lshlrev_b32_e32 v180, 3, v108
	v_lshl_add_u64 v[100:101], s[14:15], 0, v[180:181]
	v_lshlrev_b32_e32 v180, 3, v159
	v_lshl_add_u64 v[100:101], v[100:101], 0, v[180:181]
	global_load_dwordx4 v[104:107], v[100:101], off offset:16
	s_nop 0
	global_load_dwordx4 v[100:103], v[100:101], off
	s_mov_b64 s[28:29], 0
	s_waitcnt vmcnt(0)
	v_pk_mul_f32 v[110:111], v[96:97], v[100:101] op_sel:[1,1] op_sel_hi:[1,0]
	s_nop 0
	v_pk_fma_f32 v[112:113], v[96:97], v[100:101], v[110:111] neg_lo:[0,0,1] neg_hi:[0,0,1]
	v_pk_fma_f32 v[100:101], v[96:97], v[100:101], v[110:111] op_sel_hi:[0,1,1]
	v_mov_b32_e32 v113, v101
	v_pk_mul_f32 v[100:101], v[146:147], v[112:113] op_sel_hi:[0,1]
	v_mul_f32_e32 v110, v99, v103
	v_mul_f32_e32 v112, v98, v103
	v_pk_fma_f32 v[110:111], v[98:99], v[102:103], v[110:111] op_sel_hi:[1,1,0] neg_lo:[0,0,1] neg_hi:[0,0,1]
	v_pk_fma_f32 v[102:103], v[98:99], v[102:103], v[112:113] op_sel:[0,1,0] op_sel_hi:[1,0,0]
	s_nop 0
	v_mov_b32_e32 v111, v103
	v_pk_mul_f32 v[102:103], v[146:147], v[110:111] op_sel_hi:[0,1]
	v_pk_mul_f32 v[110:111], v[92:93], v[104:105] op_sel:[1,1] op_sel_hi:[1,0]
	s_nop 0
	v_pk_fma_f32 v[112:113], v[92:93], v[104:105], v[110:111] neg_lo:[0,0,1] neg_hi:[0,0,1]
	v_pk_fma_f32 v[104:105], v[92:93], v[104:105], v[110:111] op_sel_hi:[0,1,1]
	v_mov_b32_e32 v113, v105
	v_pk_mul_f32 v[104:105], v[146:147], v[112:113] op_sel_hi:[0,1]
	v_mul_f32_e32 v110, v95, v107
	v_mul_f32_e32 v112, v94, v107
	v_pk_fma_f32 v[110:111], v[94:95], v[106:107], v[110:111] op_sel_hi:[1,1,0] neg_lo:[0,0,1] neg_hi:[0,0,1]
	v_pk_fma_f32 v[106:107], v[94:95], v[106:107], v[112:113] op_sel:[0,1,0] op_sel_hi:[1,0,0]
	s_nop 0
	v_mov_b32_e32 v111, v107
	v_pk_mul_f32 v[106:107], v[146:147], v[110:111] op_sel_hi:[0,1]

.LBB0_736:
	v_mov_b64_e32 v[92:93], s[12:13]
	v_mad_i64_i32 v[92:93], s[0:1], v109, s2, v[92:93]
	v_lshl_add_u64 v[92:93], v[124:125], 1, v[92:93]
	v_cvt_pk_bf16_f32 v94, v100, v101
	v_cvt_pk_bf16_f32 v95, v102, v103
	v_cvt_pk_bf16_f32 v96, v104, v105
	v_cvt_pk_bf16_f32 v97, v106, v107
	s_cmp_lt_i32 s19, 2
	s_mov_b64 s[28:29], -1
	global_store_dwordx4 v[92:93], v[94:97], off nt
	s_cbranch_scc1 .LBB0_742
	s_cmp_gt_i32 s19, 2
	s_cbranch_scc0 .LBB0_739
	v_lshlrev_b32_e32 v180, 3, v108
	v_lshl_add_u64 v[94:95], s[14:15], 0, v[180:181]
	v_lshlrev_b32_e32 v180, 3, v159
	v_lshl_add_u64 v[94:95], v[94:95], 0, v[180:181]
	global_load_dwordx4 v[98:101], v[94:95], off offset:16
	s_nop 0
	global_load_dwordx4 v[94:97], v[94:95], off
	s_mov_b64 s[28:29], 0
	s_waitcnt vmcnt(0)
	v_pk_mul_f32 v[102:103], v[88:89], v[94:95] op_sel:[1,1] op_sel_hi:[1,0]
	s_nop 0
	v_pk_fma_f32 v[104:105], v[88:89], v[94:95], v[102:103] neg_lo:[0,0,1] neg_hi:[0,0,1]
	v_pk_fma_f32 v[94:95], v[88:89], v[94:95], v[102:103] op_sel_hi:[0,1,1]
	v_mov_b32_e32 v105, v95
	v_pk_mul_f32 v[94:95], v[146:147], v[104:105] op_sel_hi:[0,1]
	v_mul_f32_e32 v102, v91, v97
	v_mul_f32_e32 v104, v90, v97
	v_pk_fma_f32 v[102:103], v[90:91], v[96:97], v[102:103] op_sel_hi:[1,1,0] neg_lo:[0,0,1] neg_hi:[0,0,1]
	v_pk_fma_f32 v[96:97], v[90:91], v[96:97], v[104:105] op_sel:[0,1,0] op_sel_hi:[1,0,0]
	s_nop 0
	v_mov_b32_e32 v103, v97
	v_pk_mul_f32 v[96:97], v[146:147], v[102:103] op_sel_hi:[0,1]
	v_pk_mul_f32 v[102:103], v[84:85], v[98:99] op_sel:[1,1] op_sel_hi:[1,0]
	s_nop 0
	v_pk_fma_f32 v[104:105], v[84:85], v[98:99], v[102:103] neg_lo:[0,0,1] neg_hi:[0,0,1]
	v_pk_fma_f32 v[98:99], v[84:85], v[98:99], v[102:103] op_sel_hi:[0,1,1]
	v_mov_b32_e32 v105, v99
	v_pk_mul_f32 v[98:99], v[146:147], v[104:105] op_sel_hi:[0,1]
	v_mul_f32_e32 v102, v87, v101
	v_mul_f32_e32 v104, v86, v101
	v_pk_fma_f32 v[102:103], v[86:87], v[100:101], v[102:103] op_sel_hi:[1,1,0] neg_lo:[0,0,1] neg_hi:[0,0,1]
	v_pk_fma_f32 v[100:101], v[86:87], v[100:101], v[104:105] op_sel:[0,1,0] op_sel_hi:[1,0,0]
	s_nop 0
	v_mov_b32_e32 v103, v101
	v_pk_mul_f32 v[100:101], v[146:147], v[102:103] op_sel_hi:[0,1]

.LBB0_746:
	v_cvt_pk_bf16_f32 v84, v94, v95
	v_cvt_pk_bf16_f32 v85, v96, v97
	v_cvt_pk_bf16_f32 v86, v98, v99
	v_cvt_pk_bf16_f32 v87, v100, v101
	global_store_dwordx4 v[92:93], v[84:87], off offset:256 nt
	s_cmp_lt_i32 s19, 2
	s_mov_b64 s[28:29], -1
	v_mov_b32_e32 v84, v160
	s_nop 0
	v_add3_u32 v84, v84, s4, 48
	v_bitop3_b32 v85, v84, s86, v254 bitop3:0x6c
	v_cmp_gt_i32_e32 vcc, s86, v84
	v_add_u32_e32 v85, 0x100, v85
	s_nop 0
	v_cndmask_b32_sdwa v85, v85, v84, vcc dst_sel:DWORD dst_unused:UNUSED_PAD src0_sel:DWORD src1_sel:BYTE_0
	v_lshlrev_b32_e32 v94, 5, v85
	s_cbranch_scc1 .LBB0_752
	s_cmp_gt_i32 s19, 2
	s_cbranch_scc0 .LBB0_749
	v_lshlrev_b32_e32 v180, 3, v94
	v_lshl_add_u64 v[86:87], s[14:15], 0, v[180:181]
	v_lshlrev_b32_e32 v180, 3, v159
	v_lshl_add_u64 v[86:87], v[86:87], 0, v[180:181]
	global_load_dwordx4 v[90:93], v[86:87], off offset:16
	s_nop 0
	global_load_dwordx4 v[86:89], v[86:87], off
	s_mov_b64 s[28:29], 0
	s_waitcnt vmcnt(0)
	v_pk_mul_f32 v[96:97], v[80:81], v[86:87] op_sel:[1,1] op_sel_hi:[1,0]
	s_nop 0
	v_pk_fma_f32 v[98:99], v[80:81], v[86:87], v[96:97] neg_lo:[0,0,1] neg_hi:[0,0,1]
	v_pk_fma_f32 v[86:87], v[80:81], v[86:87], v[96:97] op_sel_hi:[0,1,1]
	v_mov_b32_e32 v99, v87
	v_pk_mul_f32 v[86:87], v[146:147], v[98:99] op_sel_hi:[0,1]
	v_mul_f32_e32 v96, v83, v89
	v_mul_f32_e32 v98, v82, v89
	v_pk_fma_f32 v[96:97], v[82:83], v[88:89], v[96:97] op_sel_hi:[1,1,0] neg_lo:[0,0,1] neg_hi:[0,0,1]
	v_pk_fma_f32 v[88:89], v[82:83], v[88:89], v[98:99] op_sel:[0,1,0] op_sel_hi:[1,0,0]
	s_nop 0
	v_mov_b32_e32 v97, v89
	v_pk_mul_f32 v[88:89], v[146:147], v[96:97] op_sel_hi:[0,1]
	v_pk_mul_f32 v[96:97], v[76:77], v[90:91] op_sel:[1,1] op_sel_hi:[1,0]
	s_nop 0
	v_pk_fma_f32 v[98:99], v[76:77], v[90:91], v[96:97] neg_lo:[0,0,1] neg_hi:[0,0,1]
	v_pk_fma_f32 v[90:91], v[76:77], v[90:91], v[96:97] op_sel_hi:[0,1,1]
	v_mov_b32_e32 v99, v91
	v_pk_mul_f32 v[90:91], v[146:147], v[98:99] op_sel_hi:[0,1]
	v_mul_f32_e32 v96, v79, v93
	v_mul_f32_e32 v98, v78, v93
	v_pk_fma_f32 v[96:97], v[78:79], v[92:93], v[96:97] op_sel_hi:[1,1,0] neg_lo:[0,0,1] neg_hi:[0,0,1]
	v_pk_fma_f32 v[92:93], v[78:79], v[92:93], v[98:99] op_sel:[0,1,0] op_sel_hi:[1,0,0]
	s_nop 0
	v_mov_b32_e32 v97, v93
	v_pk_mul_f32 v[92:93], v[146:147], v[96:97] op_sel_hi:[0,1]

.LBB0_756:
	v_mov_b64_e32 v[76:77], s[12:13]
	v_mad_i64_i32 v[76:77], s[0:1], v84, s2, v[76:77]
	v_lshl_add_u64 v[84:85], v[124:125], 1, v[76:77]
	v_cvt_pk_bf16_f32 v76, v86, v87
	v_cvt_pk_bf16_f32 v77, v88, v89
	v_cvt_pk_bf16_f32 v78, v90, v91
	v_cvt_pk_bf16_f32 v79, v92, v93
	s_cmp_lt_i32 s19, 2
	s_mov_b64 s[28:29], -1
	global_store_dwordx4 v[84:85], v[76:79], off nt
	s_cbranch_scc1 .LBB0_762
	s_cmp_gt_i32 s19, 2
	s_cbranch_scc0 .LBB0_759
	v_lshlrev_b32_e32 v180, 3, v94
	v_lshl_add_u64 v[76:77], s[14:15], 0, v[180:181]
	v_lshlrev_b32_e32 v180, 3, v159
	v_lshl_add_u64 v[76:77], v[76:77], 0, v[180:181]
	global_load_dwordx4 v[80:83], v[76:77], off offset:16
	s_nop 0
	global_load_dwordx4 v[76:79], v[76:77], off
	s_mov_b64 s[28:29], 0
	s_waitcnt vmcnt(0)
	v_pk_mul_f32 v[86:87], v[72:73], v[76:77] op_sel:[1,1] op_sel_hi:[1,0]
	s_nop 0
	v_pk_fma_f32 v[88:89], v[72:73], v[76:77], v[86:87] neg_lo:[0,0,1] neg_hi:[0,0,1]
	v_pk_fma_f32 v[76:77], v[72:73], v[76:77], v[86:87] op_sel_hi:[0,1,1]
	v_mov_b32_e32 v89, v77
	v_pk_mul_f32 v[76:77], v[146:147], v[88:89] op_sel_hi:[0,1]
	v_mul_f32_e32 v86, v75, v79
	v_mul_f32_e32 v88, v74, v79
	v_pk_fma_f32 v[86:87], v[74:75], v[78:79], v[86:87] op_sel_hi:[1,1,0] neg_lo:[0,0,1] neg_hi:[0,0,1]
	v_pk_fma_f32 v[78:79], v[74:75], v[78:79], v[88:89] op_sel:[0,1,0] op_sel_hi:[1,0,0]
	s_nop 0
	v_mov_b32_e32 v87, v79
	v_pk_mul_f32 v[78:79], v[146:147], v[86:87] op_sel_hi:[0,1]
	v_pk_mul_f32 v[86:87], v[68:69], v[80:81] op_sel:[1,1] op_sel_hi:[1,0]
	s_nop 0
	v_pk_fma_f32 v[88:89], v[68:69], v[80:81], v[86:87] neg_lo:[0,0,1] neg_hi:[0,0,1]
	v_pk_fma_f32 v[80:81], v[68:69], v[80:81], v[86:87] op_sel_hi:[0,1,1]
	v_mov_b32_e32 v89, v81
	v_pk_mul_f32 v[80:81], v[146:147], v[88:89] op_sel_hi:[0,1]
	v_mul_f32_e32 v86, v71, v83
	v_mul_f32_e32 v88, v70, v83
	v_pk_fma_f32 v[86:87], v[70:71], v[82:83], v[86:87] op_sel_hi:[1,1,0] neg_lo:[0,0,1] neg_hi:[0,0,1]
	v_pk_fma_f32 v[82:83], v[70:71], v[82:83], v[88:89] op_sel:[0,1,0] op_sel_hi:[1,0,0]
	s_nop 0
	v_mov_b32_e32 v87, v83
	v_pk_mul_f32 v[82:83], v[146:147], v[86:87] op_sel_hi:[0,1]

.LBB0_766:
	v_cvt_pk_bf16_f32 v68, v76, v77
	v_cvt_pk_bf16_f32 v69, v78, v79
	v_cvt_pk_bf16_f32 v70, v80, v81
	v_cvt_pk_bf16_f32 v71, v82, v83
	global_store_dwordx4 v[84:85], v[68:71], off offset:256 nt
	s_add_i32 s0, s4, 0x80
	s_cmp_lt_i32 s19, 2
	v_mov_b32_e32 v68, v160
	s_mov_b64 s[28:29], -1
	v_add_u32_e32 v77, s0, v68
	v_bitop3_b32 v68, v77, s86, v254 bitop3:0x6c
	v_cmp_gt_i32_e32 vcc, s86, v77
	v_add_u32_e32 v68, 0x100, v68
	s_nop 0
	v_cndmask_b32_sdwa v68, v68, v77, vcc dst_sel:DWORD dst_unused:UNUSED_PAD src0_sel:DWORD src1_sel:BYTE_0
	v_lshlrev_b32_e32 v76, 5, v68
	s_cbranch_scc1 .LBB0_772
	s_cmp_gt_i32 s19, 2
	s_cbranch_scc0 .LBB0_769
	v_lshlrev_b32_e32 v180, 3, v76
	v_lshl_add_u64 v[68:69], s[14:15], 0, v[180:181]
	v_lshlrev_b32_e32 v180, 3, v159
	v_lshl_add_u64 v[68:69], v[68:69], 0, v[180:181]
	global_load_dwordx4 v[72:75], v[68:69], off offset:16
	s_nop 0
	global_load_dwordx4 v[68:71], v[68:69], off
	s_mov_b64 s[28:29], 0
	s_waitcnt vmcnt(0)
	v_pk_mul_f32 v[78:79], v[64:65], v[68:69] op_sel:[1,1] op_sel_hi:[1,0]
	s_nop 0
	v_pk_fma_f32 v[80:81], v[64:65], v[68:69], v[78:79] neg_lo:[0,0,1] neg_hi:[0,0,1]
	v_pk_fma_f32 v[68:69], v[64:65], v[68:69], v[78:79] op_sel_hi:[0,1,1]
	v_mov_b32_e32 v81, v69
	v_pk_mul_f32 v[68:69], v[146:147], v[80:81] op_sel_hi:[0,1]
	v_mul_f32_e32 v78, v67, v71
	v_mul_f32_e32 v80, v66, v71
	v_pk_fma_f32 v[78:79], v[66:67], v[70:71], v[78:79] op_sel_hi:[1,1,0] neg_lo:[0,0,1] neg_hi:[0,0,1]
	v_pk_fma_f32 v[70:71], v[66:67], v[70:71], v[80:81] op_sel:[0,1,0] op_sel_hi:[1,0,0]
	s_nop 0
	v_mov_b32_e32 v79, v71
	v_pk_mul_f32 v[70:71], v[146:147], v[78:79] op_sel_hi:[0,1]
	v_pk_mul_f32 v[78:79], v[60:61], v[72:73] op_sel:[1,1] op_sel_hi:[1,0]
	s_nop 0
	v_pk_fma_f32 v[80:81], v[60:61], v[72:73], v[78:79] neg_lo:[0,0,1] neg_hi:[0,0,1]
	v_pk_fma_f32 v[72:73], v[60:61], v[72:73], v[78:79] op_sel_hi:[0,1,1]
	v_mov_b32_e32 v81, v73
	v_pk_mul_f32 v[72:73], v[146:147], v[80:81] op_sel_hi:[0,1]
	v_mul_f32_e32 v78, v63, v75
	v_mul_f32_e32 v80, v62, v75
	v_pk_fma_f32 v[78:79], v[62:63], v[74:75], v[78:79] op_sel_hi:[1,1,0] neg_lo:[0,0,1] neg_hi:[0,0,1]
	v_pk_fma_f32 v[74:75], v[62:63], v[74:75], v[80:81] op_sel:[0,1,0] op_sel_hi:[1,0,0]
	s_nop 0
	v_mov_b32_e32 v79, v75
	v_pk_mul_f32 v[74:75], v[146:147], v[78:79] op_sel_hi:[0,1]

.LBB0_776:
	v_mov_b64_e32 v[60:61], s[12:13]
	v_mad_i64_i32 v[60:61], s[0:1], v77, s2, v[60:61]
	v_lshl_add_u64 v[60:61], v[124:125], 1, v[60:61]
	v_cvt_pk_bf16_f32 v62, v68, v69
	v_cvt_pk_bf16_f32 v63, v70, v71
	v_cvt_pk_bf16_f32 v64, v72, v73
	v_cvt_pk_bf16_f32 v65, v74, v75
	s_cmp_lt_i32 s19, 2
	s_mov_b64 s[28:29], -1
	global_store_dwordx4 v[60:61], v[62:65], off nt
	s_cbranch_scc1 .LBB0_782
	s_cmp_gt_i32 s19, 2
	s_cbranch_scc0 .LBB0_779
	v_lshlrev_b32_e32 v180, 3, v76
	v_lshl_add_u64 v[62:63], s[14:15], 0, v[180:181]
	v_lshlrev_b32_e32 v180, 3, v159
	v_lshl_add_u64 v[62:63], v[62:63], 0, v[180:181]
	global_load_dwordx4 v[66:69], v[62:63], off offset:16
	s_nop 0
	global_load_dwordx4 v[62:65], v[62:63], off
	s_mov_b64 s[28:29], 0
	s_waitcnt vmcnt(0)
	v_pk_mul_f32 v[70:71], v[56:57], v[62:63] op_sel:[1,1] op_sel_hi:[1,0]
	s_nop 0
	v_pk_fma_f32 v[72:73], v[56:57], v[62:63], v[70:71] neg_lo:[0,0,1] neg_hi:[0,0,1]
	v_pk_fma_f32 v[62:63], v[56:57], v[62:63], v[70:71] op_sel_hi:[0,1,1]
	v_mov_b32_e32 v73, v63
	v_pk_mul_f32 v[62:63], v[146:147], v[72:73] op_sel_hi:[0,1]
	v_mul_f32_e32 v70, v59, v65
	v_mul_f32_e32 v72, v58, v65
	v_pk_fma_f32 v[70:71], v[58:59], v[64:65], v[70:71] op_sel_hi:[1,1,0] neg_lo:[0,0,1] neg_hi:[0,0,1]
	v_pk_fma_f32 v[64:65], v[58:59], v[64:65], v[72:73] op_sel:[0,1,0] op_sel_hi:[1,0,0]
	s_nop 0
	v_mov_b32_e32 v71, v65
	v_pk_mul_f32 v[64:65], v[146:147], v[70:71] op_sel_hi:[0,1]
	v_pk_mul_f32 v[70:71], v[52:53], v[66:67] op_sel:[1,1] op_sel_hi:[1,0]
	s_nop 0
	v_pk_fma_f32 v[72:73], v[52:53], v[66:67], v[70:71] neg_lo:[0,0,1] neg_hi:[0,0,1]
	v_pk_fma_f32 v[66:67], v[52:53], v[66:67], v[70:71] op_sel_hi:[0,1,1]
	v_mov_b32_e32 v73, v67
	v_pk_mul_f32 v[66:67], v[146:147], v[72:73] op_sel_hi:[0,1]
	v_mul_f32_e32 v70, v55, v69
	v_mul_f32_e32 v72, v54, v69
	v_pk_fma_f32 v[70:71], v[54:55], v[68:69], v[70:71] op_sel_hi:[1,1,0] neg_lo:[0,0,1] neg_hi:[0,0,1]
	v_pk_fma_f32 v[68:69], v[54:55], v[68:69], v[72:73] op_sel:[0,1,0] op_sel_hi:[1,0,0]
	s_nop 0
	v_mov_b32_e32 v71, v69
	v_pk_mul_f32 v[68:69], v[146:147], v[70:71] op_sel_hi:[0,1]

.LBB0_786:
	v_cvt_pk_bf16_f32 v52, v62, v63
	v_cvt_pk_bf16_f32 v53, v64, v65
	v_cvt_pk_bf16_f32 v54, v66, v67
	v_cvt_pk_bf16_f32 v55, v68, v69
	global_store_dwordx4 v[60:61], v[52:55], off offset:256 nt
	s_add_i32 s0, s4, 0x90
	s_cmp_lt_i32 s19, 2
	v_mov_b32_e32 v52, v160
	s_mov_b64 s[28:29], -1
	v_add_u32_e32 v61, s0, v52
	v_bitop3_b32 v52, v61, s86, v254 bitop3:0x6c
	v_cmp_gt_i32_e32 vcc, s86, v61
	v_add_u32_e32 v52, 0x100, v52
	s_nop 0
	v_cndmask_b32_sdwa v52, v52, v61, vcc dst_sel:DWORD dst_unused:UNUSED_PAD src0_sel:DWORD src1_sel:BYTE_0
	v_lshlrev_b32_e32 v60, 5, v52
	s_cbranch_scc1 .LBB0_792
	s_cmp_gt_i32 s19, 2
	s_cbranch_scc0 .LBB0_789
	v_lshlrev_b32_e32 v180, 3, v60
	v_lshl_add_u64 v[52:53], s[14:15], 0, v[180:181]
	v_lshlrev_b32_e32 v180, 3, v159
	v_lshl_add_u64 v[52:53], v[52:53], 0, v[180:181]
	global_load_dwordx4 v[56:59], v[52:53], off offset:16
	s_nop 0
	global_load_dwordx4 v[52:55], v[52:53], off
	s_mov_b64 s[28:29], 0
	s_waitcnt vmcnt(0)
	v_pk_mul_f32 v[62:63], v[48:49], v[52:53] op_sel:[1,1] op_sel_hi:[1,0]
	s_nop 0
	v_pk_fma_f32 v[64:65], v[48:49], v[52:53], v[62:63] neg_lo:[0,0,1] neg_hi:[0,0,1]
	v_pk_fma_f32 v[52:53], v[48:49], v[52:53], v[62:63] op_sel_hi:[0,1,1]
	v_mov_b32_e32 v65, v53
	v_pk_mul_f32 v[52:53], v[146:147], v[64:65] op_sel_hi:[0,1]
	v_mul_f32_e32 v62, v51, v55
	v_mul_f32_e32 v64, v50, v55
	v_pk_fma_f32 v[62:63], v[50:51], v[54:55], v[62:63] op_sel_hi:[1,1,0] neg_lo:[0,0,1] neg_hi:[0,0,1]
	v_pk_fma_f32 v[54:55], v[50:51], v[54:55], v[64:65] op_sel:[0,1,0] op_sel_hi:[1,0,0]
	s_nop 0
	v_mov_b32_e32 v63, v55
	v_pk_mul_f32 v[54:55], v[146:147], v[62:63] op_sel_hi:[0,1]
	v_pk_mul_f32 v[62:63], v[44:45], v[56:57] op_sel:[1,1] op_sel_hi:[1,0]
	s_nop 0
	v_pk_fma_f32 v[64:65], v[44:45], v[56:57], v[62:63] neg_lo:[0,0,1] neg_hi:[0,0,1]
	v_pk_fma_f32 v[56:57], v[44:45], v[56:57], v[62:63] op_sel_hi:[0,1,1]
	v_mov_b32_e32 v65, v57
	v_pk_mul_f32 v[56:57], v[146:147], v[64:65] op_sel_hi:[0,1]
	v_mul_f32_e32 v62, v47, v59
	v_mul_f32_e32 v64, v46, v59
	v_pk_fma_f32 v[62:63], v[46:47], v[58:59], v[62:63] op_sel_hi:[1,1,0] neg_lo:[0,0,1] neg_hi:[0,0,1]
	v_pk_fma_f32 v[58:59], v[46:47], v[58:59], v[64:65] op_sel:[0,1,0] op_sel_hi:[1,0,0]
	s_nop 0
	v_mov_b32_e32 v63, v59
	v_pk_mul_f32 v[58:59], v[146:147], v[62:63] op_sel_hi:[0,1]

.LBB0_796:
	v_mov_b64_e32 v[44:45], s[12:13]
	v_mad_i64_i32 v[44:45], s[0:1], v61, s2, v[44:45]
	v_lshl_add_u64 v[44:45], v[124:125], 1, v[44:45]
	v_cvt_pk_bf16_f32 v46, v52, v53
	v_cvt_pk_bf16_f32 v47, v54, v55
	v_cvt_pk_bf16_f32 v48, v56, v57
	v_cvt_pk_bf16_f32 v49, v58, v59
	s_cmp_lt_i32 s19, 2
	s_mov_b64 s[28:29], -1
	global_store_dwordx4 v[44:45], v[46:49], off nt
	s_cbranch_scc1 .LBB0_802
	s_cmp_gt_i32 s19, 2
	s_cbranch_scc0 .LBB0_799
	v_lshlrev_b32_e32 v180, 3, v60
	v_lshl_add_u64 v[46:47], s[14:15], 0, v[180:181]
	v_lshlrev_b32_e32 v180, 3, v159
	v_lshl_add_u64 v[46:47], v[46:47], 0, v[180:181]
	global_load_dwordx4 v[50:53], v[46:47], off offset:16
	s_nop 0
	global_load_dwordx4 v[46:49], v[46:47], off
	s_mov_b64 s[28:29], 0
	s_waitcnt vmcnt(0)
	v_pk_mul_f32 v[54:55], v[40:41], v[46:47] op_sel:[1,1] op_sel_hi:[1,0]
	s_nop 0
	v_pk_fma_f32 v[56:57], v[40:41], v[46:47], v[54:55] neg_lo:[0,0,1] neg_hi:[0,0,1]
	v_pk_fma_f32 v[46:47], v[40:41], v[46:47], v[54:55] op_sel_hi:[0,1,1]
	v_mov_b32_e32 v57, v47
	v_pk_mul_f32 v[46:47], v[146:147], v[56:57] op_sel_hi:[0,1]
	v_mul_f32_e32 v54, v43, v49
	v_mul_f32_e32 v56, v42, v49
	v_pk_fma_f32 v[54:55], v[42:43], v[48:49], v[54:55] op_sel_hi:[1,1,0] neg_lo:[0,0,1] neg_hi:[0,0,1]
	v_pk_fma_f32 v[48:49], v[42:43], v[48:49], v[56:57] op_sel:[0,1,0] op_sel_hi:[1,0,0]
	s_nop 0
	v_mov_b32_e32 v55, v49
	v_pk_mul_f32 v[48:49], v[146:147], v[54:55] op_sel_hi:[0,1]
	v_pk_mul_f32 v[54:55], v[36:37], v[50:51] op_sel:[1,1] op_sel_hi:[1,0]
	s_nop 0
	v_pk_fma_f32 v[56:57], v[36:37], v[50:51], v[54:55] neg_lo:[0,0,1] neg_hi:[0,0,1]
	v_pk_fma_f32 v[50:51], v[36:37], v[50:51], v[54:55] op_sel_hi:[0,1,1]
	v_mov_b32_e32 v57, v51
	v_pk_mul_f32 v[50:51], v[146:147], v[56:57] op_sel_hi:[0,1]
	v_mul_f32_e32 v54, v39, v53
	v_mul_f32_e32 v56, v38, v53
	v_pk_fma_f32 v[54:55], v[38:39], v[52:53], v[54:55] op_sel_hi:[1,1,0] neg_lo:[0,0,1] neg_hi:[0,0,1]
	v_pk_fma_f32 v[52:53], v[38:39], v[52:53], v[56:57] op_sel:[0,1,0] op_sel_hi:[1,0,0]
	s_nop 0
	v_mov_b32_e32 v55, v53
	v_pk_mul_f32 v[52:53], v[146:147], v[54:55] op_sel_hi:[0,1]

.LBB0_806:
	v_cvt_pk_bf16_f32 v36, v46, v47
	v_cvt_pk_bf16_f32 v37, v48, v49
	v_cvt_pk_bf16_f32 v38, v50, v51
	v_cvt_pk_bf16_f32 v39, v52, v53
	global_store_dwordx4 v[44:45], v[36:39], off offset:256 nt
	s_add_i32 s0, s4, 0xa0
	s_cmp_lt_i32 s19, 2
	v_mov_b32_e32 v36, v160
	s_mov_b64 s[28:29], -1
	v_add_u32_e32 v45, s0, v36
	v_bitop3_b32 v36, v45, s86, v254 bitop3:0x6c
	v_cmp_gt_i32_e32 vcc, s86, v45
	v_add_u32_e32 v36, 0x100, v36
	s_nop 0
	v_cndmask_b32_sdwa v36, v36, v45, vcc dst_sel:DWORD dst_unused:UNUSED_PAD src0_sel:DWORD src1_sel:BYTE_0
	v_lshlrev_b32_e32 v44, 5, v36
	s_cbranch_scc1 .LBB0_812
	s_cmp_gt_i32 s19, 2
	s_cbranch_scc0 .LBB0_809
	v_lshlrev_b32_e32 v180, 3, v44
	v_lshl_add_u64 v[36:37], s[14:15], 0, v[180:181]
	v_lshlrev_b32_e32 v180, 3, v159
	v_lshl_add_u64 v[36:37], v[36:37], 0, v[180:181]
	global_load_dwordx4 v[40:43], v[36:37], off offset:16
	s_nop 0
	global_load_dwordx4 v[36:39], v[36:37], off
	s_mov_b64 s[28:29], 0
	s_waitcnt vmcnt(0)
	v_pk_mul_f32 v[46:47], v[32:33], v[36:37] op_sel:[1,1] op_sel_hi:[1,0]
	s_nop 0
	v_pk_fma_f32 v[48:49], v[32:33], v[36:37], v[46:47] neg_lo:[0,0,1] neg_hi:[0,0,1]
	v_pk_fma_f32 v[36:37], v[32:33], v[36:37], v[46:47] op_sel_hi:[0,1,1]
	v_mov_b32_e32 v49, v37
	v_pk_mul_f32 v[36:37], v[146:147], v[48:49] op_sel_hi:[0,1]
	v_mul_f32_e32 v46, v35, v39
	v_mul_f32_e32 v48, v34, v39
	v_pk_fma_f32 v[46:47], v[34:35], v[38:39], v[46:47] op_sel_hi:[1,1,0] neg_lo:[0,0,1] neg_hi:[0,0,1]
	v_pk_fma_f32 v[38:39], v[34:35], v[38:39], v[48:49] op_sel:[0,1,0] op_sel_hi:[1,0,0]
	s_nop 0
	v_mov_b32_e32 v47, v39
	v_pk_mul_f32 v[38:39], v[146:147], v[46:47] op_sel_hi:[0,1]
	v_pk_mul_f32 v[46:47], v[28:29], v[40:41] op_sel:[1,1] op_sel_hi:[1,0]
	s_nop 0
	v_pk_fma_f32 v[48:49], v[28:29], v[40:41], v[46:47] neg_lo:[0,0,1] neg_hi:[0,0,1]
	v_pk_fma_f32 v[40:41], v[28:29], v[40:41], v[46:47] op_sel_hi:[0,1,1]
	v_mov_b32_e32 v49, v41
	v_pk_mul_f32 v[40:41], v[146:147], v[48:49] op_sel_hi:[0,1]
	v_mul_f32_e32 v46, v31, v43
	v_mul_f32_e32 v48, v30, v43
	v_pk_fma_f32 v[46:47], v[30:31], v[42:43], v[46:47] op_sel_hi:[1,1,0] neg_lo:[0,0,1] neg_hi:[0,0,1]
	v_pk_fma_f32 v[42:43], v[30:31], v[42:43], v[48:49] op_sel:[0,1,0] op_sel_hi:[1,0,0]
	s_nop 0
	v_mov_b32_e32 v47, v43
	v_pk_mul_f32 v[42:43], v[146:147], v[46:47] op_sel_hi:[0,1]

.LBB0_816:
	v_mov_b64_e32 v[28:29], s[12:13]
	v_mad_i64_i32 v[28:29], s[0:1], v45, s2, v[28:29]
	v_lshl_add_u64 v[28:29], v[124:125], 1, v[28:29]
	v_cvt_pk_bf16_f32 v30, v36, v37
	v_cvt_pk_bf16_f32 v31, v38, v39
	v_cvt_pk_bf16_f32 v32, v40, v41
	v_cvt_pk_bf16_f32 v33, v42, v43
	s_cmp_lt_i32 s19, 2
	s_mov_b64 s[28:29], -1
	global_store_dwordx4 v[28:29], v[30:33], off nt
	s_cbranch_scc1 .LBB0_822
	s_cmp_gt_i32 s19, 2
	s_cbranch_scc0 .LBB0_819
	v_lshlrev_b32_e32 v180, 3, v44
	v_lshl_add_u64 v[30:31], s[14:15], 0, v[180:181]
	v_lshlrev_b32_e32 v180, 3, v159
	v_lshl_add_u64 v[30:31], v[30:31], 0, v[180:181]
	global_load_dwordx4 v[34:37], v[30:31], off offset:16
	s_nop 0
	global_load_dwordx4 v[30:33], v[30:31], off
	s_mov_b64 s[28:29], 0
	s_waitcnt vmcnt(0)
	v_pk_mul_f32 v[38:39], v[24:25], v[30:31] op_sel:[1,1] op_sel_hi:[1,0]
	s_nop 0
	v_pk_fma_f32 v[40:41], v[24:25], v[30:31], v[38:39] neg_lo:[0,0,1] neg_hi:[0,0,1]
	v_pk_fma_f32 v[30:31], v[24:25], v[30:31], v[38:39] op_sel_hi:[0,1,1]
	v_mov_b32_e32 v41, v31
	v_pk_mul_f32 v[30:31], v[146:147], v[40:41] op_sel_hi:[0,1]
	v_mul_f32_e32 v38, v27, v33
	v_mul_f32_e32 v40, v26, v33
	v_pk_fma_f32 v[38:39], v[26:27], v[32:33], v[38:39] op_sel_hi:[1,1,0] neg_lo:[0,0,1] neg_hi:[0,0,1]
	v_pk_fma_f32 v[32:33], v[26:27], v[32:33], v[40:41] op_sel:[0,1,0] op_sel_hi:[1,0,0]
	s_nop 0
	v_mov_b32_e32 v39, v33
	v_pk_mul_f32 v[32:33], v[146:147], v[38:39] op_sel_hi:[0,1]
	v_pk_mul_f32 v[38:39], v[20:21], v[34:35] op_sel:[1,1] op_sel_hi:[1,0]
	s_nop 0
	v_pk_fma_f32 v[40:41], v[20:21], v[34:35], v[38:39] neg_lo:[0,0,1] neg_hi:[0,0,1]
	v_pk_fma_f32 v[34:35], v[20:21], v[34:35], v[38:39] op_sel_hi:[0,1,1]
	v_mov_b32_e32 v41, v35
	v_pk_mul_f32 v[34:35], v[146:147], v[40:41] op_sel_hi:[0,1]
	v_mul_f32_e32 v38, v23, v37
	v_mul_f32_e32 v40, v22, v37
	v_pk_fma_f32 v[38:39], v[22:23], v[36:37], v[38:39] op_sel_hi:[1,1,0] neg_lo:[0,0,1] neg_hi:[0,0,1]
	v_pk_fma_f32 v[36:37], v[22:23], v[36:37], v[40:41] op_sel:[0,1,0] op_sel_hi:[1,0,0]
	s_nop 0
	v_mov_b32_e32 v39, v37
	v_pk_mul_f32 v[36:37], v[146:147], v[38:39] op_sel_hi:[0,1]

.LBB0_826:
	v_cvt_pk_bf16_f32 v20, v30, v31
	v_cvt_pk_bf16_f32 v21, v32, v33
	v_cvt_pk_bf16_f32 v22, v34, v35
	v_cvt_pk_bf16_f32 v23, v36, v37
	global_store_dwordx4 v[28:29], v[20:23], off offset:256 nt
	s_addk_i32 s4, 0xb0
	s_cmp_lt_i32 s19, 2
	v_add_u32_e32 v29, s4, v160
	v_bitop3_b32 v20, v29, s86, v254 bitop3:0x6c
	v_cmp_gt_i32_e32 vcc, s86, v29
	v_add_u32_e32 v20, 0x100, v20
	s_mov_b64 s[28:29], -1
	v_cndmask_b32_sdwa v20, v20, v29, vcc dst_sel:DWORD dst_unused:UNUSED_PAD src0_sel:DWORD src1_sel:BYTE_0
	v_lshlrev_b32_e32 v28, 5, v20
	s_cbranch_scc1 .LBB0_832
	s_cmp_gt_i32 s19, 2
	s_cbranch_scc0 .LBB0_829
	v_lshlrev_b32_e32 v180, 3, v28
	v_lshl_add_u64 v[20:21], s[14:15], 0, v[180:181]
	v_lshlrev_b32_e32 v180, 3, v159
	v_lshl_add_u64 v[20:21], v[20:21], 0, v[180:181]
	global_load_dwordx4 v[24:27], v[20:21], off offset:16
	s_nop 0
	global_load_dwordx4 v[20:23], v[20:21], off
	s_mov_b64 s[28:29], 0
	s_waitcnt vmcnt(0)
	v_pk_mul_f32 v[30:31], v[16:17], v[20:21] op_sel:[1,1] op_sel_hi:[1,0]
	s_nop 0
	v_pk_fma_f32 v[32:33], v[16:17], v[20:21], v[30:31] neg_lo:[0,0,1] neg_hi:[0,0,1]
	v_pk_fma_f32 v[20:21], v[16:17], v[20:21], v[30:31] op_sel_hi:[0,1,1]
	v_mov_b32_e32 v33, v21
	v_pk_mul_f32 v[20:21], v[146:147], v[32:33] op_sel_hi:[0,1]
	v_mul_f32_e32 v30, v19, v23
	v_mul_f32_e32 v32, v18, v23
	v_pk_fma_f32 v[30:31], v[18:19], v[22:23], v[30:31] op_sel_hi:[1,1,0] neg_lo:[0,0,1] neg_hi:[0,0,1]
	v_pk_fma_f32 v[22:23], v[18:19], v[22:23], v[32:33] op_sel:[0,1,0] op_sel_hi:[1,0,0]
	s_nop 0
	v_mov_b32_e32 v31, v23
	v_pk_mul_f32 v[22:23], v[146:147], v[30:31] op_sel_hi:[0,1]
	v_pk_mul_f32 v[30:31], v[12:13], v[24:25] op_sel:[1,1] op_sel_hi:[1,0]
	s_nop 0
	v_pk_fma_f32 v[32:33], v[12:13], v[24:25], v[30:31] neg_lo:[0,0,1] neg_hi:[0,0,1]
	v_pk_fma_f32 v[24:25], v[12:13], v[24:25], v[30:31] op_sel_hi:[0,1,1]
	v_mov_b32_e32 v33, v25
	v_pk_mul_f32 v[24:25], v[146:147], v[32:33] op_sel_hi:[0,1]
	v_mul_f32_e32 v30, v15, v27
	v_mul_f32_e32 v32, v14, v27
	v_pk_fma_f32 v[30:31], v[14:15], v[26:27], v[30:31] op_sel_hi:[1,1,0] neg_lo:[0,0,1] neg_hi:[0,0,1]
	v_pk_fma_f32 v[26:27], v[14:15], v[26:27], v[32:33] op_sel:[0,1,0] op_sel_hi:[1,0,0]
	s_nop 0
	v_mov_b32_e32 v31, v27
	v_pk_mul_f32 v[26:27], v[146:147], v[30:31] op_sel_hi:[0,1]

.LBB0_836:
	v_mov_b64_e32 v[12:13], s[12:13]
	v_mad_i64_i32 v[12:13], s[0:1], v29, s2, v[12:13]
	v_lshl_add_u64 v[12:13], v[124:125], 1, v[12:13]
	v_cvt_pk_bf16_f32 v14, v20, v21
	v_cvt_pk_bf16_f32 v15, v22, v23
	v_cvt_pk_bf16_f32 v16, v24, v25
	v_cvt_pk_bf16_f32 v17, v26, v27
	s_cmp_lt_i32 s19, 2
	s_mov_b64 s[28:29], -1
	global_store_dwordx4 v[12:13], v[14:17], off nt
	s_cbranch_scc1 .LBB0_842
	s_cmp_gt_i32 s19, 2
	s_cbranch_scc0 .LBB0_839
	v_lshlrev_b32_e32 v180, 3, v28
	v_lshl_add_u64 v[14:15], s[14:15], 0, v[180:181]
	v_lshlrev_b32_e32 v180, 3, v159
	v_lshl_add_u64 v[14:15], v[14:15], 0, v[180:181]
	global_load_dwordx4 v[20:23], v[14:15], off offset:16
	s_nop 0
	global_load_dwordx4 v[14:17], v[14:15], off
	s_mov_b64 s[28:29], 0
	s_waitcnt vmcnt(0)
	v_pk_mul_f32 v[18:19], v[8:9], v[14:15] op_sel:[1,1] op_sel_hi:[1,0]
	s_nop 0
	v_pk_fma_f32 v[24:25], v[8:9], v[14:15], v[18:19] neg_lo:[0,0,1] neg_hi:[0,0,1]
	v_pk_fma_f32 v[14:15], v[8:9], v[14:15], v[18:19] op_sel_hi:[0,1,1]
	v_mov_b32_e32 v25, v15
	v_pk_mul_f32 v[14:15], v[146:147], v[24:25] op_sel_hi:[0,1]
	v_mul_f32_e32 v18, v11, v17
	v_mul_f32_e32 v24, v10, v17
	v_pk_fma_f32 v[18:19], v[10:11], v[16:17], v[18:19] op_sel_hi:[1,1,0] neg_lo:[0,0,1] neg_hi:[0,0,1]
	v_pk_fma_f32 v[16:17], v[10:11], v[16:17], v[24:25] op_sel:[0,1,0] op_sel_hi:[1,0,0]
	s_nop 0
	v_mov_b32_e32 v19, v17
	v_pk_mul_f32 v[16:17], v[4:5], v[20:21] op_sel:[1,1] op_sel_hi:[1,0]
	v_pk_mul_f32 v[18:19], v[146:147], v[18:19] op_sel_hi:[0,1]
	v_pk_fma_f32 v[24:25], v[4:5], v[20:21], v[16:17] neg_lo:[0,0,1] neg_hi:[0,0,1]
	v_pk_fma_f32 v[16:17], v[4:5], v[20:21], v[16:17] op_sel_hi:[0,1,1]
	v_mov_b32_e32 v25, v17
	v_pk_mul_f32 v[16:17], v[146:147], v[24:25] op_sel_hi:[0,1]
	v_mul_f32_e32 v20, v7, v23
	v_mul_f32_e32 v24, v6, v23
	v_pk_fma_f32 v[20:21], v[6:7], v[22:23], v[20:21] op_sel_hi:[1,1,0] neg_lo:[0,0,1] neg_hi:[0,0,1]
	v_pk_fma_f32 v[22:23], v[6:7], v[22:23], v[24:25] op_sel:[0,1,0] op_sel_hi:[1,0,0]
	s_nop 0
	v_mov_b32_e32 v21, v23
	v_pk_mul_f32 v[20:21], v[146:147], v[20:21] op_sel_hi:[0,1]

.LBB0_846:
	v_cvt_pk_bf16_f32 v4, v14, v15
	v_cvt_pk_bf16_f32 v5, v18, v19
	v_cvt_pk_bf16_f32 v6, v16, v17
	v_cvt_pk_bf16_f32 v7, v20, v21
	global_store_dwordx4 v[12:13], v[4:7], off offset:256 nt
	s_andn2_b64 vcc, exec, s[6:7]
	s_mov_b64 s[4:5], -1
	s_cbranch_vccnz .LBB0_667
	s_andn2_b64 vcc, exec, s[10:11]
	s_cbranch_vccnz .LBB0_666
	s_barrier
	s_branch .LBB0_666
